# v49 + next-unit queue pop issued at the end of the attention tile loop (tid 64, result held in v251) so the atomic round trip overlaps the unit epilogue
# speedup vs baseline: 1.0061x; 1.0061x over previous
; __global__ void __launch_bounds__(512, 2) hybrid_fwd(Args a) {
;     ...
;             const float* lp = a.diff_lambda + l * 256;
;             const int lane = tid & 63;
;             float v1 = lp[lane] * lp[64 + lane], v2 = lp[128 + lane] * lp[192 + lane];
; #pragma unroll
;             for (int o = 1; o < 64; o <<= 1) { v1 += __shfl_xor(v1, o); v2 += __shfl_xor(v2, o); }
;             const float lam_init = 0.8f - 0.6f * expf(-0.3f * (float)l);
;             const float lam = expf(v1) - expf(v2) + lam_init;
.LBB0_388:
	v_writelane_b32 v248, s10, 4
	s_and_b64 vcc, exec, s[0:1]
	s_nop 0
	v_writelane_b32 v248, s11, 5
	s_cbranch_vccz .LBB0_424
	v_readlane_b32 s48, v250, 2
	s_lshl_b32 s0, s12, 8
	s_lshl_b32 s1, s12, 10
	v_readlane_b32 s60, v250, 14
	v_readlane_b32 s61, v250, 15
	s_add_u32 s2, s60, s1
	v_lshlrev_b32_e32 v0, 2, v136
	s_addc_u32 s3, s61, 0
	s_waitcnt lgkmcnt(0)
	v_and_b32_e32 v5, 0xfc, v0
	global_load_dword v0, v5, s[2:3]
	global_load_dword v1, v5, s[2:3] offset:256
	global_load_dword v3, v5, s[2:3] offset:512
	global_load_dword v4, v5, s[2:3] offset:768
	v_and_b32_e32 v7, 64, v198
	v_add_u32_e32 v7, 64, v7
	v_xor_b32_e32 v8, 1, v198
	v_cmp_lt_i32_e32 vcc, v8, v7
	s_mov_b32 s2, 0x3fb8aa3b
	s_mov_b32 s3, 0xc2ce8ed0
	v_cndmask_b32_e32 v8, v198, v8, vcc
	v_lshlrev_b32_e32 v137, 2, v8
	s_mov_b32 s8, 0x42b17218
	v_readlane_b32 s56, v250, 10
	v_readlane_b32 s57, v250, 11
	v_or_b32_e32 v5, s0, v5
	v_readlane_b32 s58, v250, 12
	v_readlane_b32 s59, v250, 13
	s_mov_b32 s65, s86
	s_mov_b64 s[66:67], s[72:73]
	v_readlane_b32 s72, v250, 18
	v_readlane_b32 s73, v250, 19
	v_readlane_b32 s74, v250, 20
	v_readlane_b32 s75, v250, 21
	v_readlane_b32 s76, v250, 22
	v_readlane_b32 s77, v250, 23
	v_readlane_b32 s78, v250, 24
	v_readlane_b32 s79, v250, 25
	v_readlane_b32 s80, v250, 26
	v_readlane_b32 s81, v250, 27
	v_readlane_b32 s82, v250, 28
	v_readlane_b32 s83, v250, 29
	v_readlane_b32 s84, v250, 30
	v_readlane_b32 s85, v250, 31
	v_readlane_b32 s86, v250, 32
	v_readlane_b32 s87, v250, 33
	v_readlane_b32 s62, v250, 16
	v_readlane_b32 s49, v250, 3
	v_readlane_b32 s50, v250, 4
	v_readlane_b32 s51, v250, 5
	v_readlane_b32 s52, v250, 6
	v_readlane_b32 s53, v250, 7
	v_readlane_b32 s54, v250, 8
	v_readlane_b32 s55, v250, 9
	v_readlane_b32 s63, v250, 17
	s_mov_b32 s6, 0
	v_cmp_gt_i32_e64 s[36:37], 64, v136
	v_readlane_b32 s17, v249, 48
	v_writelane_b32 v248, s12, 6
	s_waitcnt vmcnt(2)
	v_mul_f32_e32 v2, v0, v1
	ds_bpermute_b32 v2, v137, v2
	s_waitcnt vmcnt(0)
	v_mul_f32_e32 v6, v3, v4
	s_waitcnt lgkmcnt(0)
	v_fmac_f32_e32 v2, v0, v1
	ds_bpermute_b32 v0, v137, v6
	v_xor_b32_e32 v1, 2, v198
	v_cmp_lt_i32_e32 vcc, v1, v7
	s_waitcnt lgkmcnt(0)
	v_fmac_f32_e32 v0, v3, v4
	v_cndmask_b32_e32 v1, v198, v1, vcc
	v_lshlrev_b32_e32 v4, 2, v1
	ds_bpermute_b32 v1, v4, v2
	s_waitcnt lgkmcnt(0)
	v_add_f32_e32 v1, v2, v1
	ds_bpermute_b32 v2, v4, v0
	s_waitcnt lgkmcnt(0)
	v_add_f32_e32 v0, v0, v2
	v_xor_b32_e32 v2, 4, v198
	v_cmp_lt_i32_e32 vcc, v2, v7
	s_nop 1
	v_cndmask_b32_e32 v2, v198, v2, vcc
	v_lshlrev_b32_e32 v3, 2, v2
	ds_bpermute_b32 v2, v3, v1
	s_waitcnt lgkmcnt(0)
	v_add_f32_e32 v1, v1, v2
	ds_bpermute_b32 v2, v3, v0
	s_waitcnt lgkmcnt(0)
	v_add_f32_e32 v0, v0, v2
	v_xor_b32_e32 v2, 8, v198
	v_cmp_lt_i32_e32 vcc, v2, v7
	s_nop 1
	v_cndmask_b32_e32 v2, v198, v2, vcc
	v_lshlrev_b32_e32 v2, 2, v2
	ds_bpermute_b32 v6, v2, v1
	s_waitcnt lgkmcnt(0)
	v_add_f32_e32 v1, v1, v6
	ds_bpermute_b32 v6, v2, v0
	s_waitcnt lgkmcnt(0)
	v_add_f32_e32 v0, v0, v6
	v_xor_b32_e32 v6, 16, v198
	v_cmp_lt_i32_e32 vcc, v6, v7
	s_nop 1
	v_cndmask_b32_e32 v6, v198, v6, vcc
	v_lshlrev_b32_e32 v172, 2, v6
	ds_bpermute_b32 v6, v172, v1
	s_waitcnt lgkmcnt(0)
	v_add_f32_e32 v1, v1, v6
	ds_bpermute_b32 v6, v172, v0
	s_waitcnt lgkmcnt(0)
	v_add_f32_e32 v0, v0, v6
	v_xor_b32_e32 v6, 32, v198
	v_cmp_lt_i32_e32 vcc, v6, v7
	s_nop 1
	v_cndmask_b32_e32 v6, v198, v6, vcc
	v_lshlrev_b32_e32 v173, 2, v6
	ds_bpermute_b32 v6, v173, v1
	s_waitcnt lgkmcnt(0)
	v_add_f32_e32 v1, v1, v6
	ds_bpermute_b32 v6, v173, v0
	s_waitcnt lgkmcnt(0)
; __global__ void __launch_bounds__(512, 2) hybrid_fwd(Args a) {
;     ...
;             float v1 = lp[lane] * lp[64 + lane], v2 = lp[128 + lane] * lp[192 + lane];
; #pragma unroll
;             for (int o = 1; o < 64; o <<= 1) { v1 += __shfl_xor(v1, o); v2 += __shfl_xor(v2, o); }
;             const float lam_init = 0.8f - 0.6f * expf(-0.3f * (float)l);
;             const float lam = expf(v1) - expf(v2) + lam_init;
;             float gq = fabsf(a.q_norm_g[l * 64 + lane]), gk = fabsf(a.k_norm_g[l * 64 + lane]);
; #pragma unroll
;             for (int o = 1; o < 64; o <<= 1) { gq = fmaxf(gq, __shfl_xor(gq, o)); gk = fmaxf(gk, __shfl_xor(gk, o)); }
;             const float smax = 8.0f * gq * gk * 1.01f;
;             const int xcc = (int)(__builtin_amdgcn_s_getreg((3 << 11) | 20) & 7u);
;             int it = 0;
;             unsigned* ctr = (unsigned*)(ws + WS_CTR) + l * 512;
;             unsigned live = 0xffu;
	v_add_f32_e32 v6, v0, v6
	v_cvt_f32_ubyte0_e32 v0, s12
	v_mul_f32_e32 v0, 0xbe99999a, v0
	v_mul_f32_e32 v7, 0x3fb8aa3b, v0
	v_fma_f32 v8, v0, s2, -v7
	v_rndne_f32_e32 v9, v7
	v_fmac_f32_e32 v8, 0x32a5705f, v0
	v_sub_f32_e32 v7, v7, v9
	v_add_f32_e32 v7, v7, v8
	v_exp_f32_e32 v7, v7
	v_cvt_i32_f32_e32 v8, v9
	v_cmp_ngt_f32_e32 vcc, s3, v0
	v_ldexp_f32 v7, v7, v8
	s_nop 0
	v_cndmask_b32_e32 v7, 0, v7, vcc
	v_cmp_nlt_f32_e32 vcc, s8, v0
	s_nop 1
	v_cndmask_b32_e32 v0, v199, v7, vcc
	v_mul_f32_e32 v7, 0x3fb8aa3b, v1
	v_fma_f32 v8, v1, s2, -v7
	v_rndne_f32_e32 v9, v7
	v_fmac_f32_e32 v8, 0x32a5705f, v1
	v_sub_f32_e32 v7, v7, v9
	v_add_f32_e32 v7, v7, v8
	v_exp_f32_e32 v7, v7
	v_cvt_i32_f32_e32 v8, v9
	v_cmp_ngt_f32_e32 vcc, s3, v1
	v_fmamk_f32 v0, v0, 0xbf19999a, v196
	v_sub_f32_e32 v176, 1.0, v0
	v_ldexp_f32 v7, v7, v8
	v_cndmask_b32_e32 v7, 0, v7, vcc
	v_cmp_nlt_f32_e32 vcc, s8, v1
	s_nop 1
	v_cndmask_b32_e32 v1, v199, v7, vcc
	v_mul_f32_e32 v7, 0x3fb8aa3b, v6
	v_fma_f32 v8, v6, s2, -v7
	v_rndne_f32_e32 v9, v7
	v_fmac_f32_e32 v8, 0x32a5705f, v6
	v_sub_f32_e32 v7, v7, v9
	v_add_f32_e32 v7, v7, v8
	v_exp_f32_e32 v7, v7
	v_cvt_i32_f32_e32 v8, v9
	v_cmp_ngt_f32_e32 vcc, s3, v6
	s_lshl_b32 s2, s12, 11
	v_readlane_b32 s3, v250, 38
	v_ldexp_f32 v7, v7, v8
	v_cndmask_b32_e32 v7, 0, v7, vcc
	v_cmp_nlt_f32_e32 vcc, s8, v6
	s_lshl_b32 s8, s12, 9
	s_add_u32 s44, s3, s2
	v_cndmask_b32_e32 v6, v199, v7, vcc
	v_sub_f32_e32 v1, v1, v6
	global_load_dword v6, v5, s[56:57]
	v_readlane_b32 s2, v250, 39
	global_load_dword v5, v5, s[58:59]
	s_addc_u32 s45, s2, 0
	s_lshl_b32 s2, s12, 14
	s_add_u32 s24, s72, s2
	v_readlane_b32 s72, v250, 18
	v_readlane_b32 s73, v250, 19
	v_readlane_b32 s74, v250, 20
	v_readlane_b32 s75, v250, 21
	v_readlane_b32 s76, v250, 22
	v_readlane_b32 s77, v250, 23
	v_readlane_b32 s78, v250, 24
	v_readlane_b32 s79, v250, 25
	v_readlane_b32 s80, v250, 26
	v_readlane_b32 s81, v250, 27
	v_readlane_b32 s82, v250, 28
	v_readlane_b32 s83, v250, 29
	v_readlane_b32 s84, v250, 30
	v_readlane_b32 s85, v250, 31
	v_readlane_b32 s86, v250, 32
	v_readlane_b32 s87, v250, 33
	s_addc_u32 s25, s73, 0
	v_readlane_b32 s72, v250, 18
	v_readlane_b32 s73, v250, 19
	v_readlane_b32 s74, v250, 20
	v_readlane_b32 s75, v250, 21
	v_readlane_b32 s76, v250, 22
	v_readlane_b32 s77, v250, 23
	v_readlane_b32 s78, v250, 24
	v_readlane_b32 s79, v250, 25
	v_readlane_b32 s80, v250, 26
	v_readlane_b32 s81, v250, 27
	v_readlane_b32 s82, v250, 28
	v_readlane_b32 s83, v250, 29
	v_readlane_b32 s84, v250, 30
	v_readlane_b32 s85, v250, 31
	v_readlane_b32 s86, v250, 32
	v_readlane_b32 s87, v250, 33
	s_add_u32 s2, s74, s1
	v_readlane_b32 s72, v250, 18
	v_readlane_b32 s73, v250, 19
	v_readlane_b32 s74, v250, 20
	v_readlane_b32 s75, v250, 21
	v_readlane_b32 s76, v250, 22
	v_readlane_b32 s77, v250, 23
	v_readlane_b32 s78, v250, 24
	v_readlane_b32 s79, v250, 25
	v_readlane_b32 s80, v250, 26
	v_readlane_b32 s81, v250, 27
	v_readlane_b32 s82, v250, 28
	v_readlane_b32 s83, v250, 29
	v_readlane_b32 s84, v250, 30
	v_readlane_b32 s85, v250, 31
	v_readlane_b32 s86, v250, 32
	v_readlane_b32 s87, v250, 33
	s_addc_u32 s3, s75, 0
	v_readlane_b32 s72, v250, 18
	v_readlane_b32 s73, v250, 19
	v_readlane_b32 s74, v250, 20
	v_readlane_b32 s75, v250, 21
	v_readlane_b32 s76, v250, 22
	v_readlane_b32 s77, v250, 23
	v_readlane_b32 s78, v250, 24
	v_readlane_b32 s79, v250, 25
	v_readlane_b32 s80, v250, 26
	v_readlane_b32 s81, v250, 27
	v_readlane_b32 s82, v250, 28
	v_readlane_b32 s83, v250, 29
	v_readlane_b32 s84, v250, 30
	v_readlane_b32 s85, v250, 31
	v_readlane_b32 s86, v250, 32
	v_readlane_b32 s87, v250, 33
	s_add_u32 s20, s76, s0
	v_readlane_b32 s72, v250, 18
	v_readlane_b32 s77, v250, 23
	v_add_f32_e32 v174, v0, v1
	s_addc_u32 s21, s77, 0
	s_getreg_b32 s16, hwreg(HW_REG_XCC_ID, 0, 4)
	s_add_u32 s26, s62, s8
	s_waitcnt vmcnt(1)
	v_and_b32_e32 v7, 0x7fffffff, v6
	ds_bpermute_b32 v7, v137, v7
	s_waitcnt vmcnt(0)
	v_and_b32_e32 v8, 0x7fffffff, v5
	v_max_f32_e64 v6, |v6|, |v6|
	v_max_f32_e64 v5, |v5|, |v5|
	s_addc_u32 s27, s63, 0
	s_waitcnt lgkmcnt(0)
	v_max_f32_e32 v7, v7, v7
	v_max_f32_e32 v6, v6, v7
	ds_bpermute_b32 v7, v137, v8
	v_readlane_b32 s48, v250, 18
	v_readlane_b32 s79, v250, 25
	v_readlane_b32 s81, v250, 27
	v_readlane_b32 s82, v250, 28
	s_waitcnt lgkmcnt(0)
	v_max_f32_e32 v7, v7, v7
	v_max_f32_e32 v5, v5, v7
	ds_bpermute_b32 v7, v4, v6
	ds_bpermute_b32 v4, v4, v5
	v_readlane_b32 s52, v250, 22
	s_mov_b32 s79, 0x3d800000
	v_readlane_b32 s49, v250, 19
	s_waitcnt lgkmcnt(1)
	v_max_f32_e32 v7, v7, v7
	v_max_f32_e32 v6, v6, v7
	s_waitcnt lgkmcnt(0)
	v_max_f32_e32 v4, v4, v4
	v_max_f32_e32 v4, v5, v4
	ds_bpermute_b32 v5, v3, v6
	ds_bpermute_b32 v3, v3, v4
	v_readlane_b32 s50, v250, 20
	v_readlane_b32 s51, v250, 21
	v_readlane_b32 s62, v250, 32
	s_waitcnt lgkmcnt(1)
	v_max_f32_e32 v5, v5, v5
	v_max_f32_e32 v5, v6, v5
	s_waitcnt lgkmcnt(0)
	v_max_f32_e32 v3, v3, v3
	v_max_f32_e32 v3, v4, v3
	ds_bpermute_b32 v4, v2, v5
	ds_bpermute_b32 v2, v2, v3
	v_readlane_b32 s63, v250, 33
	s_movk_i32 s82, 0xff
	s_mov_b32 s81, 0
	s_waitcnt lgkmcnt(1)
	v_max_f32_e32 v4, v4, v4
	v_max_f32_e32 v4, v5, v4
	s_waitcnt lgkmcnt(0)
	v_max_f32_e32 v2, v2, v2
	v_max_f32_e32 v2, v3, v2
	ds_bpermute_b32 v3, v172, v4
	s_movk_i32 s52, 0xe00
	v_readlane_b32 s73, v250, 19
	v_readlane_b32 s74, v250, 20
	v_readlane_b32 s75, v250, 21
	s_waitcnt lgkmcnt(0)
	v_max_f32_e32 v3, v3, v3
	v_max_f32_e32 v3, v4, v3
	ds_bpermute_b32 v4, v172, v2
	v_readlane_b32 s76, v250, 22
	v_readlane_b32 s78, v250, 24
	v_readlane_b32 s80, v250, 26
	v_readlane_b32 s83, v250, 29
	s_waitcnt lgkmcnt(0)
	v_max_f32_e32 v4, v4, v4
	v_max_f32_e32 v2, v2, v4
	ds_bpermute_b32 v4, v173, v3
	v_readlane_b32 s84, v250, 30
	v_readlane_b32 s85, v250, 31
	v_readlane_b32 s86, v250, 32
	v_readlane_b32 s87, v250, 33
	s_waitcnt lgkmcnt(0)
	v_max_f32_e32 v4, v4, v4
	v_max_f32_e32 v3, v3, v4
	ds_bpermute_b32 v4, v173, v2
	v_mul_f32_e32 v1, 0x41000000, v3
	v_readlane_b32 s53, v250, 23
	v_readlane_b32 s54, v250, 24
	v_readlane_b32 s55, v250, 25
	s_waitcnt lgkmcnt(0)
	v_max_f32_e32 v4, v4, v4
	v_max_f32_e32 v2, v2, v4
	v_mul_f32_e32 v1, v2, v1
	v_subrev_co_u32_e64 v2, s[38:39], 1, v136
	v_cmp_gt_u32_e64 s[40:41], 7, v2
	v_add_lshl_u32 v2, s16, v136, 8
	v_mul_f32_e32 v1, 0x3f8147ae, v1
	v_and_b32_e32 v156, 0x700, v2
	v_lshl_add_u64 v[116:117], s[44:45], 0, v[156:157]
	v_fmaak_f32 v175, 2.0, v1, 0x42d00000
	v_readlane_b32 s56, v250, 26
	v_readlane_b32 s57, v250, 27
	v_readlane_b32 s58, v250, 28
	v_readlane_b32 s59, v250, 29
	v_readlane_b32 s60, v250, 30
	v_readlane_b32 s61, v250, 31
	v_mov_b32_e32 v251, -1
	s_branch .LBB0_392

; #define LAS __attribute__((address_space(3)))
; #define LAS __attribute__((address_space(3)))
; __global__ void __launch_bounds__(512, 2) hybrid_fwd(Args a) {
;     ...
;                     const ldsp slot = lds + LDS_PHASE + 16 + (it & 1) * 4;
;                     if (tid == 0) *(LAS unsigned*)slot = __hip_atomic_fetch_add(ctr + xq * 64, 1u, __ATOMIC_RELAXED, __HIP_MEMORY_SCOPE_AGENT);
;                     __syncthreads();
;                     const int idx = (int)*(LAS unsigned*)slot;
.LBB0_403:
	s_lshl_b32 s0, s6, 2
	s_mov_b32 s87, s6
	s_and_b32 s6, s0, 4
	v_cmp_eq_u32_e64 s[100:101], 64, v136
	s_and_saveexec_b64 s[0:1], s[100:101]
	s_cbranch_execz .LBB0_407
	s_waitcnt vmcnt(0)
	v_cmp_ne_u32_e32 vcc, -1, v251
	s_cbranch_vccnz .Lpop_have
	v_mov_b32_e32 v251, 1
	global_atomic_add v251, v157, v251, s[76:77] sc0
	s_waitcnt vmcnt(0)
.Lpop_have:
	v_mov_b32_e32 v0, v251
	v_mov_b32_e32 v251, -1
	s_add_i32 s8, s6, 0
	s_add_i32 s8, s8, 0x20010
	v_mov_b32_e32 v1, s8
	ds_write_b32 v1, v0

; #define LAS __attribute__((address_space(3)))
; #define LAS __attribute__((address_space(3)))
; DI void attn_unit(const bf16_t* z, const bf16_t* VT, bf16_t* Y, const float* subg, ldsp lds, int tid, int b, int h, int qb, float lam, float ns, float oscale, int win) {
;     ...
;     ls0 += __shfl_xor(ls0, 16); ls0 += __shfl_xor(ls0, 32);
;     ls1 += __shfl_xor(ls1, 16); ls1 += __shfl_xor(ls1, 32);
;     const float sc0 = comp ? lam / ls0 : 1.0f / ls0, sc1 = comp ? lam / ls1 : 1.0f / ls1;
;     const ldsp xp = lds + g * 16384 + lane * 4;
;     if (comp) {
; #pragma unroll
;         for (int e = 0; e < 8; ++e)
; #pragma unroll
;             for (int qt = 0; qt < 2; ++qt)
; #pragma unroll
;                 for (int r = 0; r < 4; ++r) *(LAS float*)(xp + ((2 * e + qt) * 4 + r) * 256) = O[e][qt][r] * (qt ? sc1 : sc0);
;     }
.Lat_exit:
.LBB0_419:
	s_or_b64 exec, exec, s[28:29]
	s_mov_b64 s[100:101], exec
	v_cmp_eq_u32_e32 vcc, 64, v136
	s_and_b64 exec, exec, vcc
	v_mov_b32_e32 v251, 1
	global_atomic_add v251, v157, v251, s[76:77] sc0
	s_mov_b64 exec, s[100:101]
	ds_bpermute_b32 v57, v172, v129
	ds_bpermute_b32 v56, v172, v128
	s_cmp_eq_u32 s9, 0
	s_cselect_b64 s[0:1], -1, 0
	s_lshl_b32 s8, s8, 14
	s_add_i32 s8, s8, 0
	s_waitcnt lgkmcnt(0)
	v_pk_add_f32 v[56:57], v[128:129], v[56:57]
	ds_bpermute_b32 v59, v173, v57
	ds_bpermute_b32 v58, v173, v56
	v_ashrrev_i32_e32 v121, 31, v120
	v_ashrrev_i32_e32 v119, 31, v118
	v_lshl_add_u32 v70, v178, 2, s8
	s_waitcnt lgkmcnt(0)
	v_pk_add_f32 v[56:57], v[56:57], v[58:59]
	v_cndmask_b32_e64 v58, v174, 1.0, s[0:1]
	v_div_scale_f32 v59, s[10:11], v57, v57, v58
	v_rcp_f32_e32 v60, v59
	s_nop 0
	v_fma_f32 v61, -v59, v60, 1.0
	v_fmac_f32_e32 v60, v61, v60
	v_div_scale_f32 v61, vcc, v58, v57, v58
	v_mul_f32_e32 v62, v61, v60
	v_fma_f32 v63, -v59, v62, v61
	v_fmac_f32_e32 v62, v63, v60
	v_fma_f32 v59, -v59, v62, v61
	v_div_fmas_f32 v59, v59, v60, v62
	v_div_fixup_f32 v57, v59, v57, v58
	v_div_scale_f32 v59, s[10:11], v56, v56, v58
	v_rcp_f32_e32 v60, v59
	s_nop 0
	v_fma_f32 v61, -v59, v60, 1.0
	v_fmac_f32_e32 v60, v61, v60
	v_div_scale_f32 v61, vcc, v58, v56, v58
	v_mul_f32_e32 v62, v61, v60
	v_fma_f32 v63, -v59, v62, v61
	v_fmac_f32_e32 v62, v63, v60
	v_fma_f32 v59, -v59, v62, v61
	v_div_fmas_f32 v59, v59, v60, v62
	v_div_fixup_f32 v56, v59, v56, v58
	s_and_b64 vcc, exec, s[0:1]
	s_cbranch_vccnz .LBB0_421
	v_mul_f32_e32 v58, v72, v57
	v_mul_f32_e32 v59, v73, v57
	ds_write2st64_b32 v70, v58, v59 offset1:1
	v_mul_f32_e32 v58, v74, v57
	v_mul_f32_e32 v59, v75, v57
	ds_write2st64_b32 v70, v58, v59 offset0:2 offset1:3
	v_mul_f32_e32 v58, v76, v56
	v_mul_f32_e32 v59, v77, v56
	ds_write2st64_b32 v70, v58, v59 offset0:4 offset1:5
	v_mul_f32_e32 v58, v78, v56
	v_mul_f32_e32 v59, v79, v56
	ds_write2st64_b32 v70, v58, v59 offset0:6 offset1:7
	v_mul_f32_e32 v58, v52, v57
	v_mul_f32_e32 v59, v53, v57
	ds_write2st64_b32 v70, v58, v59 offset0:8 offset1:9
	v_mul_f32_e32 v58, v54, v57
	v_mul_f32_e32 v59, v55, v57
	ds_write2st64_b32 v70, v58, v59 offset0:10 offset1:11
	v_mul_f32_e32 v58, v48, v56
	v_mul_f32_e32 v59, v49, v56
	ds_write2st64_b32 v70, v58, v59 offset0:12 offset1:13
	v_mul_f32_e32 v58, v50, v56
	v_mul_f32_e32 v59, v51, v56
	ds_write2st64_b32 v70, v58, v59 offset0:14 offset1:15
	v_mul_f32_e32 v58, v44, v57
	v_mul_f32_e32 v59, v45, v57
	ds_write2st64_b32 v70, v58, v59 offset0:16 offset1:17
	v_mul_f32_e32 v58, v46, v57
	v_mul_f32_e32 v59, v47, v57
	ds_write2st64_b32 v70, v58, v59 offset0:18 offset1:19
	v_mul_f32_e32 v58, v40, v56
	v_mul_f32_e32 v59, v41, v56
	ds_write2st64_b32 v70, v58, v59 offset0:20 offset1:21
	v_mul_f32_e32 v58, v42, v56
	v_mul_f32_e32 v59, v43, v56
	ds_write2st64_b32 v70, v58, v59 offset0:22 offset1:23
	v_mul_f32_e32 v58, v36, v57
	v_mul_f32_e32 v59, v37, v57
	ds_write2st64_b32 v70, v58, v59 offset0:24 offset1:25
	v_mul_f32_e32 v58, v38, v57
	v_mul_f32_e32 v59, v39, v57
	ds_write2st64_b32 v70, v58, v59 offset0:26 offset1:27
	v_mul_f32_e32 v58, v32, v56
	v_mul_f32_e32 v59, v33, v56
	ds_write2st64_b32 v70, v58, v59 offset0:28 offset1:29
	v_mul_f32_e32 v58, v34, v56
	v_mul_f32_e32 v59, v35, v56
	ds_write2st64_b32 v70, v58, v59 offset0:30 offset1:31
	v_mul_f32_e32 v58, v28, v57
	v_mul_f32_e32 v59, v29, v57
	ds_write2st64_b32 v70, v58, v59 offset0:32 offset1:33
	v_mul_f32_e32 v58, v30, v57
	v_mul_f32_e32 v59, v31, v57
	ds_write2st64_b32 v70, v58, v59 offset0:34 offset1:35
	v_mul_f32_e32 v58, v20, v56
	v_mul_f32_e32 v59, v21, v56
	ds_write2st64_b32 v70, v58, v59 offset0:36 offset1:37
	v_mul_f32_e32 v58, v22, v56
	v_mul_f32_e32 v59, v23, v56
	ds_write2st64_b32 v70, v58, v59 offset0:38 offset1:39
	v_mul_f32_e32 v58, v16, v57
	v_mul_f32_e32 v59, v17, v57
	ds_write2st64_b32 v70, v58, v59 offset0:40 offset1:41
	v_mul_f32_e32 v58, v18, v57
	v_mul_f32_e32 v59, v19, v57
	ds_write2st64_b32 v70, v58, v59 offset0:42 offset1:43
	v_mul_f32_e32 v58, v12, v56
	v_mul_f32_e32 v59, v13, v56
	ds_write2st64_b32 v70, v58, v59 offset0:44 offset1:45
	v_mul_f32_e32 v58, v14, v56
	v_mul_f32_e32 v59, v15, v56
	ds_write2st64_b32 v70, v58, v59 offset0:46 offset1:47
	v_mul_f32_e32 v58, v24, v57
	v_mul_f32_e32 v59, v25, v57
	ds_write2st64_b32 v70, v58, v59 offset0:48 offset1:49
	v_mul_f32_e32 v58, v26, v57
	v_mul_f32_e32 v59, v27, v57
	ds_write2st64_b32 v70, v58, v59 offset0:50 offset1:51
	v_mul_f32_e32 v58, v8, v56
	v_mul_f32_e32 v59, v9, v56
	ds_write2st64_b32 v70, v58, v59 offset0:52 offset1:53
	v_mul_f32_e32 v58, v10, v56
	v_mul_f32_e32 v59, v11, v56
	ds_write2st64_b32 v70, v58, v59 offset0:54 offset1:55
	v_mul_f32_e32 v58, v4, v57
	v_mul_f32_e32 v59, v5, v57
	ds_write2st64_b32 v70, v58, v59 offset0:56 offset1:57
	v_mul_f32_e32 v58, v6, v57
	v_mul_f32_e32 v59, v7, v57
	ds_write2st64_b32 v70, v58, v59 offset0:58 offset1:59
	v_mul_f32_e32 v58, v0, v56
	v_mul_f32_e32 v59, v1, v56
	ds_write2st64_b32 v70, v58, v59 offset0:60 offset1:61
	v_mul_f32_e32 v58, v2, v56
	v_mul_f32_e32 v59, v3, v56
	ds_write2st64_b32 v70, v58, v59 offset0:62 offset1:63

; __global__ void __launch_bounds__(512, 2) hybrid_fwd(Args a) {
;     extern __shared__ __attribute__((aligned(16))) unsigned char lds_raw[];
	.amdhsa_kernel _Z10hybrid_fwd4Args
		.amdhsa_group_segment_fixed_size 0
		.amdhsa_private_segment_fixed_size 0
		.amdhsa_kernarg_size 392
		.amdhsa_user_sgpr_count 2
		.amdhsa_user_sgpr_dispatch_ptr 0
		.amdhsa_user_sgpr_queue_ptr 0
		.amdhsa_user_sgpr_kernarg_segment_ptr 1
		.amdhsa_user_sgpr_dispatch_id 0
		.amdhsa_user_sgpr_kernarg_preload_length 0
		.amdhsa_user_sgpr_kernarg_preload_offset 0
		.amdhsa_user_sgpr_private_segment_size 0
		.amdhsa_uses_dynamic_stack 0
		.amdhsa_enable_private_segment 0
		.amdhsa_system_sgpr_workgroup_id_x 1
		.amdhsa_system_sgpr_workgroup_id_y 0
		.amdhsa_system_sgpr_workgroup_id_z 0
		.amdhsa_system_sgpr_workgroup_info 0
		.amdhsa_system_vgpr_workitem_id 2
		.amdhsa_next_free_vgpr 252
		.amdhsa_next_free_sgpr 102
		.amdhsa_accum_offset 252
		.amdhsa_reserve_vcc 1
		.amdhsa_float_round_mode_32 0
		.amdhsa_float_round_mode_16_64 0
		.amdhsa_float_denorm_mode_32 3
		.amdhsa_float_denorm_mode_16_64 3
		.amdhsa_dx10_clamp 1
		.amdhsa_ieee_mode 1
		.amdhsa_fp16_overflow 0
		.amdhsa_tg_split 0
		.amdhsa_exception_fp_ieee_invalid_op 0
		.amdhsa_exception_fp_denorm_src 0
		.amdhsa_exception_fp_ieee_div_zero 0
		.amdhsa_exception_fp_ieee_overflow 0
		.amdhsa_exception_fp_ieee_underflow 0
		.amdhsa_exception_fp_ieee_inexact 0
		.amdhsa_exception_int_div_zero 0
	.end_amdhsa_kernel

; __global__ void __launch_bounds__(512, 2) hybrid_fwd(Args a) {
;     extern __shared__ __attribute__((aligned(16))) unsigned char lds_raw[];
amdhsa.kernels:
  - .agpr_count:     0
    .args:
      - .offset:         0
        .size:           136
        .value_kind:     by_value
      - .offset:         136
        .size:           4
        .value_kind:     hidden_block_count_x
      - .offset:         140
        .size:           4
        .value_kind:     hidden_block_count_y
      - .offset:         144
        .size:           4
        .value_kind:     hidden_block_count_z
      - .offset:         148
        .size:           2
        .value_kind:     hidden_group_size_x
      - .offset:         150
        .size:           2
        .value_kind:     hidden_group_size_y
      - .offset:         152
        .size:           2
        .value_kind:     hidden_group_size_z
      - .offset:         154
        .size:           2
        .value_kind:     hidden_remainder_x
      - .offset:         156
        .size:           2
        .value_kind:     hidden_remainder_y
      - .offset:         158
        .size:           2
        .value_kind:     hidden_remainder_z
      - .offset:         176
        .size:           8
        .value_kind:     hidden_global_offset_x
      - .offset:         184
        .size:           8
        .value_kind:     hidden_global_offset_y
      - .offset:         192
        .size:           8
        .value_kind:     hidden_global_offset_z
      - .offset:         200
        .size:           2
        .value_kind:     hidden_grid_dims
      - .offset:         224
        .size:           8
        .value_kind:     hidden_multigrid_sync_arg
      - .offset:         256
        .size:           4
        .value_kind:     hidden_dynamic_lds_size
    .group_segment_fixed_size: 0
    .kernarg_segment_align: 8
    .kernarg_segment_size: 392
    .language:       OpenCL C
    .language_version:
      - 2
      - 0
    .max_flat_workgroup_size: 512
    .name:           _Z10hybrid_fwd4Args
    .private_segment_fixed_size: 0
    .sgpr_count:     108
    .sgpr_spill_count: 149
    .symbol:         _Z10hybrid_fwd4Args.kd
    .uniform_work_group_size: 1
    .uses_dynamic_stack: false
    .vgpr_count:     252
    .vgpr_spill_count: 0
    .wavefront_size: 64
